# conv units of the attention phase software-pipelined (next item's loads issued before current item's transpose/pack/store) + P7 batched loads
# speedup vs baseline: 1.0050x; 1.0050x over previous
.LBB0_357:
	s_andn2_b64 vcc, exec, s[14:15]
	s_cbranch_vccnz .LBB0_280
	v_mov_b32_e32 v6, v0
	s_cmp_eq_u32 s2, 6
	v_lshlrev_b32_e32 v4, 2, v6
	v_bfe_u32 v3, v6, 4, 2
	v_and_b32_e32 v4, 60, v4
	s_cselect_b64 s[4:5], -1, 0
	s_lshl_b32 s2, s50, 1
	v_mul_u32_u24_e32 v5, 0x104, v3
	v_lshlrev_b32_e32 v7, 2, v4
	v_cndmask_b32_e64 v8, 0, 1, s[4:5]
	v_add3_u32 v5, s88, v5, v7
	v_bfe_u32 v7, v6, 3, 3
	v_lshlrev_b32_e32 v6, 3, v6
	s_cmp_lg_u64 s[4:5], 0
	v_and_b32_e32 v6, 56, v6
	s_addc_u32 s2, s89, s2
	s_mulk_i32 s50, 0x4800
	v_readfirstlane_b32 s5, v8
	v_mul_u32_u24_e32 v9, 0x104, v6
	v_lshlrev_b32_e32 v10, 2, v7
	s_mul_i32 s4, s2, 0x90
	s_add_i32 s48, s42, s50
	s_mulk_i32 s5, 0x2400
	s_add_i32 s49, s40, s50
	v_add3_u32 v10, s88, v9, v10
	v_or_b32_e32 v11, 8, v7
	v_or_b32_e32 v12, 16, v7
	v_or_b32_e32 v13, 24, v7
	v_or_b32_e32 v14, 32, v7
	v_or_b32_e32 v15, 40, v7
	v_or_b32_e32 v16, 48, v7
	v_or_b32_e32 v17, 56, v7
	v_lshlrev_b32_e32 v18, 14, v3
	s_add_i32 s2, s76, s4
	s_add_i32 s48, s48, s5
	s_add_i32 s49, s49, s5
	s_add_i32 s50, s91, s4
	s_mov_b32 s51, 0
	s_load_dwordx2 s[78:79], s[0:1], 0x70
	s_load_dwordx2 s[80:81], s[0:1], 0x80
	s_load_dwordx2 s[82:83], s[0:1], 0x88
	s_waitcnt lgkmcnt(0)
	s_mov_b32 s41, s2
	s_mov_b64 s[10:11], s[78:79]
	s_mov_b32 s43, 12
	s_cmpk_lt_i32 s41, 0x1000
	s_cbranch_scc1 .Lcv_d_p
	s_mov_b64 s[10:11], s[80:81]
	s_mov_b32 s43, 14
	s_sub_i32 s41, s41, 0x1000
	s_cmpk_lt_i32 s41, 0x4000
	s_cbranch_scc1 .Lcv_d_p
	s_mov_b64 s[10:11], s[82:83]
	s_mov_b32 s43, 12
	s_sub_i32 s41, s41, 0x4000
.Lcv_d_p:
	s_sub_i32 s45, s43, 6
	s_lshr_b32 s47, s41, s45
	s_bfm_b32 s84, s45, 0
	s_and_b32 s84, s41, s84
	s_add_i32 s45, s43, 8
	s_lshl_b32 s47, s47, s45
	s_lshl_b32 s84, s84, 8
	s_add_u32 s47, s47, s84
	s_add_u32 s10, s10, s47
	s_addc_u32 s11, s11, 0
	s_add_i32 s45, s43, 2
	v_and_b32_e32 v165, 63, v0
	v_lshrrev_b32_e32 v164, 4, v165
	v_and_b32_e32 v165, 15, v165
	v_lshlrev_b32_e32 v164, s45, v164
	v_lshl_add_u32 v164, v165, 4, v164
	s_add_i32 s45, s43, 4
	s_lshl_b32 s47, 1, s45
	global_load_dwordx4 v[100:103], v164, s[10:11]
	s_add_u32 s10, s10, s47
	s_addc_u32 s11, s11, 0
	global_load_dwordx4 v[104:107], v164, s[10:11]
	s_add_u32 s10, s10, s47
	s_addc_u32 s11, s11, 0
	global_load_dwordx4 v[108:111], v164, s[10:11]
	s_add_u32 s10, s10, s47
	s_addc_u32 s11, s11, 0
	global_load_dwordx4 v[112:115], v164, s[10:11]
	s_add_u32 s10, s10, s47
	s_addc_u32 s11, s11, 0
	global_load_dwordx4 v[116:119], v164, s[10:11]
	s_add_u32 s10, s10, s47
	s_addc_u32 s11, s11, 0
	global_load_dwordx4 v[120:123], v164, s[10:11]
	s_add_u32 s10, s10, s47
	s_addc_u32 s11, s11, 0
	global_load_dwordx4 v[124:127], v164, s[10:11]
	s_add_u32 s10, s10, s47
	s_addc_u32 s11, s11, 0
	global_load_dwordx4 v[128:131], v164, s[10:11]
	s_add_u32 s10, s10, s47
	s_addc_u32 s11, s11, 0
	global_load_dwordx4 v[132:135], v164, s[10:11]
	s_add_u32 s10, s10, s47
	s_addc_u32 s11, s11, 0
	global_load_dwordx4 v[136:139], v164, s[10:11]
	s_add_u32 s10, s10, s47
	s_addc_u32 s11, s11, 0
	global_load_dwordx4 v[140:143], v164, s[10:11]
	s_add_u32 s10, s10, s47
	s_addc_u32 s11, s11, 0
	global_load_dwordx4 v[144:147], v164, s[10:11]
	s_add_u32 s10, s10, s47
	s_addc_u32 s11, s11, 0
	global_load_dwordx4 v[148:151], v164, s[10:11]
	s_add_u32 s10, s10, s47
	s_addc_u32 s11, s11, 0
	global_load_dwordx4 v[152:155], v164, s[10:11]
	s_add_u32 s10, s10, s47
	s_addc_u32 s11, s11, 0
	global_load_dwordx4 v[156:159], v164, s[10:11]
	s_add_u32 s10, s10, s47
	s_addc_u32 s11, s11, 0
	global_load_dwordx4 v[160:163], v164, s[10:11]
	s_branch .LBB0_360

.LBB0_360:
	s_cmpk_gt_i32 s2, 0xfff
	s_mov_b64 s[4:5], -1
	s_cbranch_scc0 .LBB0_366
	s_cmpk_gt_u32 s2, 0x4fff
	s_cbranch_scc0 .LBB0_363
	s_mov_b64 s[4:5], s[0:1]
	s_load_dwordx2 s[6:7], s[4:5], 0x88
	s_add_i32 s8, s2, 0xffffb000
	s_and_b32 s9, s8, 0xffffffc0
	s_add_i32 s16, s48, s51
	v_or_b32_e32 v8, s9, v3
	v_mov_b32_e32 v9, v2
	s_and_b32 s12, s16, 0xfc0
	v_lshlrev_b64 v[8:9], 14, v[8:9]
	s_waitcnt lgkmcnt(0)
	v_lshl_add_u64 v[8:9], s[6:7], 0, v[8:9]
	s_lshl_b32 s12, s12, 2
	v_lshl_add_u64 v[8:9], v[8:9], 0, s[12:13]
	v_lshlrev_b32_e32 v20, 2, v4
	v_mov_b32_e32 v21, v2
	v_lshl_add_u64 v[8:9], v[8:9], 0, v[20:21]
	v_add_co_u32_e32 v24, vcc, s3, v8
	s_mov_b64 s[4:5], s[0:1]
	s_nop 0
	v_addc_co_u32_e32 v25, vcc, 0, v9, vcc
	v_add_co_u32_e32 v28, vcc, s45, v8
	s_nop 0
	s_nop 0
	s_nop 0
	v_addc_co_u32_e32 v29, vcc, 0, v9, vcc
	v_add_co_u32_e32 v32, vcc, s47, v8
	s_lshr_b32 s6, s8, 6
	s_nop 0
	v_addc_co_u32_e32 v33, vcc, 0, v9, vcc
	s_nop 0
	s_nop 0
	s_nop 0
	v_add_co_u32_e32 v36, vcc, s10, v8
	s_and_b32 s7, s16, 0xf00
	s_nop 0
	v_addc_co_u32_e32 v37, vcc, 0, v9, vcc
	v_add_co_u32_e32 v40, vcc, s11, v8
	s_add_i32 s12, s7, s6
	s_nop 0
	v_addc_co_u32_e32 v41, vcc, 0, v9, vcc
	s_nop 0
	s_nop 0
	s_nop 0
	v_add_co_u32_e32 v44, vcc, s80, v8
	s_lshl_b64 s[6:7], s[12:13], 15
	s_nop 0
	v_addc_co_u32_e32 v45, vcc, 0, v9, vcc
	v_add_co_u32_e32 v48, vcc, s41, v8
	s_nop 1
	v_addc_co_u32_e32 v49, vcc, 0, v9, vcc
	s_nop 0
	s_nop 0
	s_nop 0
	v_add_co_u32_e32 v52, vcc, s43, v8
	s_nop 1
	v_addc_co_u32_e32 v53, vcc, 0, v9, vcc
	v_add_co_u32_e32 v56, vcc, s78, v8
	s_nop 1
	v_addc_co_u32_e32 v57, vcc, 0, v9, vcc
	s_nop 0
	s_nop 0
	s_nop 0
	v_add_co_u32_e32 v60, vcc, s79, v8
	s_nop 1
	v_addc_co_u32_e32 v61, vcc, 0, v9, vcc
	v_add_co_u32_e32 v64, vcc, s81, v8
	s_nop 1
	v_addc_co_u32_e32 v65, vcc, 0, v9, vcc
	s_nop 0
	s_nop 0
	s_nop 0
	v_add_co_u32_e32 v68, vcc, s82, v8
	s_load_dwordx2 s[4:5], s[4:5], 0xa0
	s_nop 0
	v_addc_co_u32_e32 v69, vcc, 0, v9, vcc
	s_nop 0
	v_add_co_u32_e32 v72, vcc, s83, v8
	s_waitcnt lgkmcnt(0)
	s_add_u32 s6, s4, s6
	v_addc_co_u32_e32 v73, vcc, 0, v9, vcc
	s_nop 0
	v_add_co_u32_e32 v76, vcc, s84, v8
	s_addc_u32 s7, s5, s7
	s_nop 0
	v_addc_co_u32_e32 v77, vcc, 0, v9, vcc
	s_nop 0
	v_add_co_u32_e32 v8, vcc, s86, v8
	s_and_b32 s4, s16, 0xc0
	s_nop 0
	v_addc_co_u32_e32 v9, vcc, 0, v9, vcc
	s_nop 0
	v_add_u32_e32 v8, 0x410, v5
	s_cselect_b32 s86, 1, 0
	s_cmpk_lg_i32 s51, 0
	s_cbranch_scc1 .Lcv_w8_a
	s_waitcnt vmcnt(0)
.Lcv_w8_a:
	s_waitcnt vmcnt(8)
	v_mov_b32_e32 v20, v100
	v_mov_b32_e32 v21, v101
	v_mov_b32_e32 v22, v102
	v_mov_b32_e32 v23, v103
	v_mov_b32_e32 v24, v104
	v_mov_b32_e32 v25, v105
	v_mov_b32_e32 v26, v106
	v_mov_b32_e32 v27, v107
	v_mov_b32_e32 v28, v108
	v_mov_b32_e32 v29, v109
	v_mov_b32_e32 v30, v110
	v_mov_b32_e32 v31, v111
	v_mov_b32_e32 v32, v112
	v_mov_b32_e32 v33, v113
	v_mov_b32_e32 v34, v114
	v_mov_b32_e32 v35, v115
	v_mov_b32_e32 v36, v116
	v_mov_b32_e32 v37, v117
	v_mov_b32_e32 v38, v118
	v_mov_b32_e32 v39, v119
	v_mov_b32_e32 v40, v120
	v_mov_b32_e32 v41, v121
	v_mov_b32_e32 v42, v122
	v_mov_b32_e32 v43, v123
	v_mov_b32_e32 v44, v124
	v_mov_b32_e32 v45, v125
	v_mov_b32_e32 v46, v126
	v_mov_b32_e32 v47, v127
	v_mov_b32_e32 v48, v128
	v_mov_b32_e32 v49, v129
	v_mov_b32_e32 v50, v130
	v_mov_b32_e32 v51, v131
	v_mov_b32_e32 v52, v132
	v_mov_b32_e32 v53, v133
	v_mov_b32_e32 v54, v134
	v_mov_b32_e32 v55, v135
	v_mov_b32_e32 v56, v136
	v_mov_b32_e32 v57, v137
	v_mov_b32_e32 v58, v138
	v_mov_b32_e32 v59, v139
	v_mov_b32_e32 v60, v140
	v_mov_b32_e32 v61, v141
	v_mov_b32_e32 v62, v142
	v_mov_b32_e32 v63, v143
	v_mov_b32_e32 v64, v144
	v_mov_b32_e32 v65, v145
	v_mov_b32_e32 v66, v146
	v_mov_b32_e32 v67, v147
	v_mov_b32_e32 v68, v148
	v_mov_b32_e32 v69, v149
	v_mov_b32_e32 v70, v150
	v_mov_b32_e32 v71, v151
	v_mov_b32_e32 v72, v152
	v_mov_b32_e32 v73, v153
	v_mov_b32_e32 v74, v154
	v_mov_b32_e32 v75, v155
	v_mov_b32_e32 v76, v156
	v_mov_b32_e32 v77, v157
	v_mov_b32_e32 v78, v158
	v_mov_b32_e32 v79, v159
	v_mov_b32_e32 v80, v160
	v_mov_b32_e32 v81, v161
	v_mov_b32_e32 v82, v162
	v_mov_b32_e32 v83, v163
	s_cmpk_eq_i32 s51, 0x2200
	s_cbranch_scc1 .Lcv_nopf_a
	s_add_i32 s41, s2, 8
	s_mov_b64 s[10:11], s[78:79]
	s_mov_b32 s43, 12
	s_cmpk_lt_i32 s41, 0x1000
	s_cbranch_scc1 .Lcv_d_a
	s_mov_b64 s[10:11], s[80:81]
	s_mov_b32 s43, 14
	s_sub_i32 s41, s41, 0x1000
	s_cmpk_lt_i32 s41, 0x4000
	s_cbranch_scc1 .Lcv_d_a
	s_mov_b64 s[10:11], s[82:83]
	s_mov_b32 s43, 12
	s_sub_i32 s41, s41, 0x4000
.Lcv_d_a:
	s_sub_i32 s45, s43, 6
	s_lshr_b32 s47, s41, s45
	s_bfm_b32 s84, s45, 0
	s_and_b32 s84, s41, s84
	s_add_i32 s45, s43, 8
	s_lshl_b32 s47, s47, s45
	s_lshl_b32 s84, s84, 8
	s_add_u32 s47, s47, s84
	s_add_u32 s10, s10, s47
	s_addc_u32 s11, s11, 0
	s_add_i32 s45, s43, 2
	v_and_b32_e32 v165, 63, v0
	v_lshrrev_b32_e32 v164, 4, v165
	v_and_b32_e32 v165, 15, v165
	v_lshlrev_b32_e32 v164, s45, v164
	v_lshl_add_u32 v164, v165, 4, v164
	s_add_i32 s45, s43, 4
	s_lshl_b32 s47, 1, s45
	global_load_dwordx4 v[100:103], v164, s[10:11]
	s_add_u32 s10, s10, s47
	s_addc_u32 s11, s11, 0
	global_load_dwordx4 v[104:107], v164, s[10:11]
	s_add_u32 s10, s10, s47
	s_addc_u32 s11, s11, 0
	global_load_dwordx4 v[108:111], v164, s[10:11]
	s_add_u32 s10, s10, s47
	s_addc_u32 s11, s11, 0
	global_load_dwordx4 v[112:115], v164, s[10:11]
	s_add_u32 s10, s10, s47
	s_addc_u32 s11, s11, 0
	global_load_dwordx4 v[116:119], v164, s[10:11]
	s_add_u32 s10, s10, s47
	s_addc_u32 s11, s11, 0
	global_load_dwordx4 v[120:123], v164, s[10:11]
	s_add_u32 s10, s10, s47
	s_addc_u32 s11, s11, 0
	global_load_dwordx4 v[124:127], v164, s[10:11]
	s_add_u32 s10, s10, s47
	s_addc_u32 s11, s11, 0
	global_load_dwordx4 v[128:131], v164, s[10:11]
	s_add_u32 s10, s10, s47
	s_addc_u32 s11, s11, 0
	global_load_dwordx4 v[132:135], v164, s[10:11]
	s_add_u32 s10, s10, s47
	s_addc_u32 s11, s11, 0
	global_load_dwordx4 v[136:139], v164, s[10:11]
	s_add_u32 s10, s10, s47
	s_addc_u32 s11, s11, 0
	global_load_dwordx4 v[140:143], v164, s[10:11]
	s_add_u32 s10, s10, s47
	s_addc_u32 s11, s11, 0
	global_load_dwordx4 v[144:147], v164, s[10:11]
	s_add_u32 s10, s10, s47
	s_addc_u32 s11, s11, 0
	global_load_dwordx4 v[148:151], v164, s[10:11]
	s_add_u32 s10, s10, s47
	s_addc_u32 s11, s11, 0
	global_load_dwordx4 v[152:155], v164, s[10:11]
	s_add_u32 s10, s10, s47
	s_addc_u32 s11, s11, 0
	global_load_dwordx4 v[156:159], v164, s[10:11]
	s_add_u32 s10, s10, s47
	s_addc_u32 s11, s11, 0
	global_load_dwordx4 v[160:163], v164, s[10:11]
.Lcv_nopf_a:
	s_cmp_lg_u32 s86, 0
	ds_write2_b32 v5, v20, v21 offset1:1
	ds_write2_b32 v5, v22, v23 offset0:2 offset1:3
	ds_write2_b32 v8, v24, v25 offset1:1
	v_add_u32_e32 v8, 0x418, v5
	ds_write2_b32 v8, v26, v27 offset1:1
	v_add_u32_e32 v8, 0x820, v5
	v_mov_b32_e32 v9, v2
	ds_write2_b32 v8, v28, v29 offset1:1
	v_add_u32_e32 v8, 0x828, v5
	ds_write2_b32 v8, v30, v31 offset1:1
	v_add_u32_e32 v8, 0xc30, v5
	ds_write2_b32 v8, v32, v33 offset1:1
	v_add_u32_e32 v8, 0xc38, v5
	ds_write2_b32 v8, v34, v35 offset1:1
	v_add_u32_e32 v8, 0x1040, v5
	ds_write2_b32 v8, v36, v37 offset1:1
	v_add_u32_e32 v8, 0x1048, v5
	ds_write2_b32 v8, v38, v39 offset1:1
	v_add_u32_e32 v8, 0x1450, v5
	ds_write2_b32 v8, v40, v41 offset1:1
	v_add_u32_e32 v8, 0x1458, v5
	ds_write2_b32 v8, v42, v43 offset1:1
	v_add_u32_e32 v8, 0x1860, v5
	v_add_u32_e32 v42, 0x400, v10
	v_mov_b32_e32 v41, v2
	ds_write2_b32 v8, v44, v45 offset1:1
	v_add_u32_e32 v8, 0x1868, v5
	ds_write2_b32 v8, v46, v47 offset1:1
	v_add_u32_e32 v8, 0x1c70, v5
	ds_write2_b32 v8, v48, v49 offset1:1
	v_add_u32_e32 v8, 0x1c78, v5
	ds_write2_b32 v8, v50, v51 offset1:1
	v_add_u32_e32 v8, 0x2080, v5
	ds_write2_b32 v8, v52, v53 offset1:1
	v_add_u32_e32 v8, 0x2088, v5
	ds_write2_b32 v8, v54, v55 offset1:1
	v_add_u32_e32 v8, 0x2490, v5
	ds_write2_b32 v8, v56, v57 offset1:1
	v_add_u32_e32 v8, 0x2498, v5
	ds_write2_b32 v8, v58, v59 offset1:1
	v_add_u32_e32 v8, 0x28a0, v5
	ds_write2_b32 v8, v60, v61 offset1:1
	v_add_u32_e32 v8, 0x28a8, v5
	ds_write2_b32 v8, v62, v63 offset1:1
	v_add_u32_e32 v8, 0x2cb0, v5
	ds_write2_b32 v8, v64, v65 offset1:1
	v_add_u32_e32 v8, 0x2cb8, v5
	ds_write2_b32 v8, v66, v67 offset1:1
	v_add_u32_e32 v8, 0x30c0, v5
	ds_write2_b32 v8, v68, v69 offset1:1
	v_add_u32_e32 v8, 0x30c8, v5
	ds_write2_b32 v8, v70, v71 offset1:1
	v_add_u32_e32 v8, 0x34d0, v5
	ds_write2_b32 v8, v72, v73 offset1:1
	v_add_u32_e32 v8, 0x34d8, v5
	ds_write2_b32 v8, v74, v75 offset1:1
	v_add_u32_e32 v8, 0x38e0, v5
	ds_write2_b32 v8, v76, v77 offset1:1
	v_add_u32_e32 v8, 0x38e8, v5
	ds_write2_b32 v8, v78, v79 offset1:1
	v_add_u32_e32 v8, 0x3cf0, v5
	ds_write2_b32 v8, v80, v81 offset1:1
	v_add_u32_e32 v8, 0x3cf8, v5
	ds_write2_b32 v8, v82, v83 offset1:1
	s_waitcnt lgkmcnt(0)
	ds_read2_b32 v[24:25], v10 offset1:8
	ds_read2_b32 v[26:27], v10 offset0:65 offset1:73
	ds_read2_b32 v[28:29], v10 offset0:130 offset1:138
	ds_read2_b32 v[30:31], v10 offset0:195 offset1:203
	ds_read2_b32 v[32:33], v42 offset0:4 offset1:12
	s_waitcnt lgkmcnt(4)
	v_bfe_u32 v19, v24, 16, 1
	v_add3_u32 v19, v24, v19, s87
	s_waitcnt lgkmcnt(3)
	v_bfe_u32 v20, v26, 16, 1
	v_lshrrev_b32_e32 v19, 16, v19
	v_add3_u32 v20, v26, v20, s87
	ds_read2_b32 v[34:35], v42 offset0:69 offset1:77
	v_and_or_b32 v20, v20, s90, v19
	s_waitcnt lgkmcnt(3)
	v_bfe_u32 v19, v28, 16, 1
	v_add3_u32 v19, v28, v19, s87
	s_waitcnt lgkmcnt(2)
	v_bfe_u32 v21, v30, 16, 1
	ds_read2_b32 v[36:37], v42 offset0:134 offset1:142
	v_lshrrev_b32_e32 v19, 16, v19
	v_add3_u32 v21, v30, v21, s87
	ds_read2_b32 v[38:39], v42 offset0:199 offset1:207
	v_and_or_b32 v21, v21, s90, v19
	s_waitcnt lgkmcnt(3)
	v_bfe_u32 v19, v32, 16, 1
	v_add3_u32 v19, v32, v19, s87
	s_waitcnt lgkmcnt(2)
	v_bfe_u32 v22, v34, 16, 1
	v_lshrrev_b32_e32 v19, 16, v19
	v_add3_u32 v22, v34, v22, s87
	v_and_or_b32 v22, v22, s90, v19
	s_waitcnt lgkmcnt(1)
	v_bfe_u32 v19, v36, 16, 1
	v_add3_u32 v19, v36, v19, s87
	s_waitcnt lgkmcnt(0)
	v_bfe_u32 v23, v38, 16, 1
	v_lshlrev_b32_e32 v8, 1, v6
	v_lshrrev_b32_e32 v19, 16, v19
	v_add3_u32 v23, v38, v23, s87
	v_lshl_add_u64 v[8:9], s[6:7], 0, v[8:9]
	s_mov_b64 s[6:7], 0x10400000
	v_and_or_b32 v23, v23, s90, v19
	v_or_b32_e32 v19, s4, v7
	v_lshl_add_u64 v[8:9], v[8:9], 0, s[6:7]
	v_lshlrev_b32_e32 v40, 7, v19
	v_lshl_add_u64 v[40:41], v[8:9], 0, v[40:41]
	v_bfe_u32 v19, v25, 16, 1
	global_store_dwordx4 v[40:41], v[20:23], off
	v_add3_u32 v19, v25, v19, s87
	v_lshrrev_b32_e32 v19, 16, v19
	v_bfe_u32 v20, v27, 16, 1
	v_add3_u32 v20, v27, v20, s87
	v_and_or_b32 v20, v20, s90, v19
	v_bfe_u32 v19, v29, 16, 1
	v_add3_u32 v19, v29, v19, s87
	v_bfe_u32 v21, v31, 16, 1
	v_lshrrev_b32_e32 v19, 16, v19
	v_add3_u32 v21, v31, v21, s87
	v_and_or_b32 v21, v21, s90, v19
	v_bfe_u32 v19, v33, 16, 1
	v_add3_u32 v19, v33, v19, s87
	v_bfe_u32 v22, v35, 16, 1
	v_lshrrev_b32_e32 v19, 16, v19
	v_add3_u32 v22, v35, v22, s87
	v_and_or_b32 v22, v22, s90, v19
	v_bfe_u32 v19, v37, 16, 1
	v_add3_u32 v19, v37, v19, s87
	v_bfe_u32 v23, v39, 16, 1
	v_lshrrev_b32_e32 v19, 16, v19
	v_add3_u32 v23, v39, v23, s87
	v_and_or_b32 v23, v23, s90, v19
	v_or_b32_e32 v19, s4, v11
	v_lshlrev_b32_e32 v24, 7, v19
	v_mov_b32_e32 v25, v2
	ds_read2_b32 v[26:27], v10 offset0:16 offset1:24
	v_lshl_add_u64 v[24:25], v[8:9], 0, v[24:25]
	global_store_dwordx4 v[24:25], v[20:23], off
	ds_read2_b32 v[24:25], v10 offset0:81 offset1:89
	ds_read2_b32 v[28:29], v10 offset0:146 offset1:154
	ds_read2_b32 v[30:31], v10 offset0:211 offset1:219
	s_waitcnt lgkmcnt(3)
	v_bfe_u32 v19, v26, 16, 1
	v_add3_u32 v19, v26, v19, s87
	s_waitcnt lgkmcnt(2)
	v_bfe_u32 v20, v24, 16, 1
	ds_read2_b32 v[32:33], v42 offset0:20 offset1:28
	v_lshrrev_b32_e32 v19, 16, v19
	v_add3_u32 v20, v24, v20, s87
	ds_read2_b32 v[34:35], v42 offset0:85 offset1:93
	v_and_or_b32 v20, v20, s90, v19
	s_waitcnt lgkmcnt(3)
	v_bfe_u32 v19, v28, 16, 1
	v_add3_u32 v19, v28, v19, s87
	s_waitcnt lgkmcnt(2)
	v_bfe_u32 v21, v30, 16, 1
	ds_read2_b32 v[36:37], v42 offset0:150 offset1:158
	v_lshrrev_b32_e32 v19, 16, v19
	v_add3_u32 v21, v30, v21, s87
	ds_read2_b32 v[38:39], v42 offset0:215 offset1:223
	v_and_or_b32 v21, v21, s90, v19
	s_waitcnt lgkmcnt(3)
	v_bfe_u32 v19, v32, 16, 1
	v_add3_u32 v19, v32, v19, s87
	s_waitcnt lgkmcnt(2)
	v_bfe_u32 v22, v34, 16, 1
	v_lshrrev_b32_e32 v19, 16, v19
	v_add3_u32 v22, v34, v22, s87
	v_and_or_b32 v22, v22, s90, v19
	s_waitcnt lgkmcnt(1)
	v_bfe_u32 v19, v36, 16, 1
	v_add3_u32 v19, v36, v19, s87
	s_waitcnt lgkmcnt(0)
	v_bfe_u32 v23, v38, 16, 1
	v_lshrrev_b32_e32 v19, 16, v19
	v_add3_u32 v23, v38, v23, s87
	v_and_or_b32 v23, v23, s90, v19
	v_or_b32_e32 v19, s4, v12
	v_lshlrev_b32_e32 v40, 7, v19
	v_mov_b32_e32 v41, v2
	v_lshl_add_u64 v[40:41], v[8:9], 0, v[40:41]
	v_bfe_u32 v19, v27, 16, 1
	global_store_dwordx4 v[40:41], v[20:23], off
	v_add3_u32 v19, v27, v19, s87
	v_lshrrev_b32_e32 v19, 16, v19
	v_bfe_u32 v20, v25, 16, 1
	v_add3_u32 v20, v25, v20, s87
	v_and_or_b32 v20, v20, s90, v19
	v_bfe_u32 v19, v29, 16, 1
	v_add3_u32 v19, v29, v19, s87
	v_bfe_u32 v21, v31, 16, 1
	v_lshrrev_b32_e32 v19, 16, v19
	v_add3_u32 v21, v31, v21, s87
	v_and_or_b32 v21, v21, s90, v19
	v_bfe_u32 v19, v33, 16, 1
	v_add3_u32 v19, v33, v19, s87
	v_bfe_u32 v22, v35, 16, 1
	v_lshrrev_b32_e32 v19, 16, v19
	v_add3_u32 v22, v35, v22, s87
	v_and_or_b32 v22, v22, s90, v19
	v_bfe_u32 v19, v37, 16, 1
	v_add3_u32 v19, v37, v19, s87
	v_bfe_u32 v23, v39, 16, 1
	v_lshrrev_b32_e32 v19, 16, v19
	v_add3_u32 v23, v39, v23, s87
	v_and_or_b32 v23, v23, s90, v19
	v_or_b32_e32 v19, s4, v13
	v_lshlrev_b32_e32 v24, 7, v19
	v_mov_b32_e32 v25, v2
	ds_read2_b32 v[26:27], v10 offset0:32 offset1:40
	v_lshl_add_u64 v[24:25], v[8:9], 0, v[24:25]
	global_store_dwordx4 v[24:25], v[20:23], off
	ds_read2_b32 v[24:25], v10 offset0:97 offset1:105
	ds_read2_b32 v[28:29], v10 offset0:162 offset1:170
	ds_read2_b32 v[30:31], v10 offset0:227 offset1:235
	s_waitcnt lgkmcnt(3)
	v_bfe_u32 v19, v26, 16, 1
	v_add3_u32 v19, v26, v19, s87
	s_waitcnt lgkmcnt(2)
	v_bfe_u32 v20, v24, 16, 1
	ds_read2_b32 v[32:33], v42 offset0:36 offset1:44
	v_lshrrev_b32_e32 v19, 16, v19
	v_add3_u32 v20, v24, v20, s87
	ds_read2_b32 v[34:35], v42 offset0:101 offset1:109
	v_and_or_b32 v20, v20, s90, v19
	s_waitcnt lgkmcnt(3)
	v_bfe_u32 v19, v28, 16, 1
	v_add3_u32 v19, v28, v19, s87
	s_waitcnt lgkmcnt(2)
	v_bfe_u32 v21, v30, 16, 1
	ds_read2_b32 v[36:37], v42 offset0:166 offset1:174
	v_lshrrev_b32_e32 v19, 16, v19
	v_add3_u32 v21, v30, v21, s87
	ds_read2_b32 v[38:39], v42 offset0:231 offset1:239
	v_and_or_b32 v21, v21, s90, v19
	s_waitcnt lgkmcnt(3)
	v_bfe_u32 v19, v32, 16, 1
	v_add3_u32 v19, v32, v19, s87
	s_waitcnt lgkmcnt(2)
	v_bfe_u32 v22, v34, 16, 1
	v_lshrrev_b32_e32 v19, 16, v19
	v_add3_u32 v22, v34, v22, s87
	v_and_or_b32 v22, v22, s90, v19
	s_waitcnt lgkmcnt(1)
	v_bfe_u32 v19, v36, 16, 1
	v_add3_u32 v19, v36, v19, s87
	s_waitcnt lgkmcnt(0)
	v_bfe_u32 v23, v38, 16, 1
	v_lshrrev_b32_e32 v19, 16, v19
	v_add3_u32 v23, v38, v23, s87
	v_and_or_b32 v23, v23, s90, v19
	v_or_b32_e32 v19, s4, v14
	v_lshlrev_b32_e32 v40, 7, v19
	v_mov_b32_e32 v41, v2
	v_lshl_add_u64 v[40:41], v[8:9], 0, v[40:41]
	v_bfe_u32 v19, v27, 16, 1
	global_store_dwordx4 v[40:41], v[20:23], off
	v_add3_u32 v19, v27, v19, s87
	v_lshrrev_b32_e32 v19, 16, v19
	v_bfe_u32 v20, v25, 16, 1
	v_add3_u32 v20, v25, v20, s87
	v_and_or_b32 v20, v20, s90, v19
	v_bfe_u32 v19, v29, 16, 1
	v_add3_u32 v19, v29, v19, s87
	v_bfe_u32 v21, v31, 16, 1
	v_lshrrev_b32_e32 v19, 16, v19
	v_add3_u32 v21, v31, v21, s87
	v_and_or_b32 v21, v21, s90, v19
	v_bfe_u32 v19, v33, 16, 1
	v_add3_u32 v19, v33, v19, s87
	v_bfe_u32 v22, v35, 16, 1
	v_lshrrev_b32_e32 v19, 16, v19
	v_add3_u32 v22, v35, v22, s87
	v_and_or_b32 v22, v22, s90, v19
	v_bfe_u32 v19, v37, 16, 1
	v_add3_u32 v19, v37, v19, s87
	v_bfe_u32 v23, v39, 16, 1
	v_lshrrev_b32_e32 v19, 16, v19
	v_add3_u32 v23, v39, v23, s87
	v_and_or_b32 v23, v23, s90, v19
	v_or_b32_e32 v19, s4, v15
	v_lshlrev_b32_e32 v24, 7, v19
	v_mov_b32_e32 v25, v2
	ds_read2_b32 v[26:27], v10 offset0:48 offset1:56
	v_lshl_add_u64 v[24:25], v[8:9], 0, v[24:25]
	global_store_dwordx4 v[24:25], v[20:23], off
	ds_read2_b32 v[24:25], v10 offset0:113 offset1:121
	ds_read2_b32 v[28:29], v10 offset0:178 offset1:186
	ds_read2_b32 v[30:31], v10 offset0:243 offset1:251
	s_waitcnt lgkmcnt(3)
	v_bfe_u32 v19, v26, 16, 1
	v_add3_u32 v19, v26, v19, s87
	s_waitcnt lgkmcnt(2)
	v_bfe_u32 v20, v24, 16, 1
	ds_read2_b32 v[32:33], v42 offset0:52 offset1:60
	v_lshrrev_b32_e32 v19, 16, v19
	v_add3_u32 v20, v24, v20, s87
	ds_read2_b32 v[34:35], v42 offset0:117 offset1:125
	v_and_or_b32 v20, v20, s90, v19
	s_waitcnt lgkmcnt(3)
	v_bfe_u32 v19, v28, 16, 1
	v_add3_u32 v19, v28, v19, s87
	s_waitcnt lgkmcnt(2)
	v_bfe_u32 v21, v30, 16, 1
	ds_read2_b32 v[36:37], v42 offset0:182 offset1:190
	v_lshrrev_b32_e32 v19, 16, v19
	v_add3_u32 v21, v30, v21, s87
	ds_read2_b32 v[38:39], v42 offset0:247 offset1:255
	v_and_or_b32 v21, v21, s90, v19
	s_waitcnt lgkmcnt(3)
	v_bfe_u32 v19, v32, 16, 1
	v_add3_u32 v19, v32, v19, s87
	s_waitcnt lgkmcnt(2)
	v_bfe_u32 v22, v34, 16, 1
	v_lshrrev_b32_e32 v19, 16, v19
	v_add3_u32 v22, v34, v22, s87
	v_and_or_b32 v22, v22, s90, v19
	s_waitcnt lgkmcnt(1)
	v_bfe_u32 v19, v36, 16, 1
	v_add3_u32 v19, v36, v19, s87
	s_waitcnt lgkmcnt(0)
	v_bfe_u32 v23, v38, 16, 1
	v_lshrrev_b32_e32 v19, 16, v19
	v_add3_u32 v23, v38, v23, s87
	v_and_or_b32 v23, v23, s90, v19
	v_or_b32_e32 v19, s4, v16
	v_lshlrev_b32_e32 v40, 7, v19
	v_mov_b32_e32 v41, v2
	v_lshl_add_u64 v[40:41], v[8:9], 0, v[40:41]
	v_bfe_u32 v19, v27, 16, 1
	global_store_dwordx4 v[40:41], v[20:23], off
	v_add3_u32 v19, v27, v19, s87
	v_lshrrev_b32_e32 v19, 16, v19
	v_bfe_u32 v20, v25, 16, 1
	v_add3_u32 v20, v25, v20, s87
	v_and_or_b32 v20, v20, s90, v19
	v_bfe_u32 v19, v29, 16, 1
	v_add3_u32 v19, v29, v19, s87
	v_bfe_u32 v21, v31, 16, 1
	v_lshrrev_b32_e32 v19, 16, v19
	v_add3_u32 v21, v31, v21, s87
	v_and_or_b32 v21, v21, s90, v19
	v_bfe_u32 v19, v33, 16, 1
	v_add3_u32 v19, v33, v19, s87
	v_bfe_u32 v22, v35, 16, 1
	v_lshrrev_b32_e32 v19, 16, v19
	v_add3_u32 v22, v35, v22, s87
	v_and_or_b32 v22, v22, s90, v19
	v_bfe_u32 v19, v37, 16, 1
	v_add3_u32 v19, v37, v19, s87
	v_bfe_u32 v23, v39, 16, 1
	v_lshrrev_b32_e32 v19, 16, v19
	v_add3_u32 v23, v39, v23, s87
	v_and_or_b32 v23, v23, s90, v19
	v_or_b32_e32 v19, s4, v17
	v_lshlrev_b32_e32 v24, 7, v19
	v_mov_b32_e32 v25, v2
	v_lshl_add_u64 v[8:9], v[8:9], 0, v[24:25]
	global_store_dwordx4 v[8:9], v[20:23], off
	s_waitcnt lgkmcnt(0)
	s_mov_b64 s[4:5], 0
.LBB0_363:
	s_andn2_b64 vcc, exec, s[4:5]
	s_cbranch_vccnz .LBB0_365
	s_lshl_b32 s4, s50, 6
	s_and_b32 s4, s4, 0xffffc000
	s_sub_i32 s12, s49, s4
	s_mov_b64 s[4:5], s[0:1]
	s_load_dwordx2 s[8:9], s[4:5], 0x80
	s_add_i32 s4, s2, 0xfffff000
	s_lshr_b32 s16, s4, 8
	s_add_i32 s4, s51, s12
	v_lshl_or_b32 v8, s16, 20, v18
	v_mov_b32_e32 v9, v2
	s_waitcnt lgkmcnt(0)
	v_lshl_add_u64 v[8:9], v[8:9], 2, s[8:9]
	s_ashr_i32 s5, s4, 31
	v_lshl_add_u64 v[8:9], s[4:5], 2, v[8:9]
	v_lshlrev_b32_e32 v20, 2, v4
	v_mov_b32_e32 v21, v2
	v_lshl_add_u64 v[8:9], v[8:9], 0, v[20:21]
	v_add_co_u32_e32 v24, vcc, s10, v8
	s_mov_b64 s[6:7], s[0:1]
	s_nop 0
	v_addc_co_u32_e32 v25, vcc, 0, v9, vcc
	v_add_co_u32_e32 v28, vcc, s43, v8
	s_nop 0
	s_nop 0
	s_nop 0
	v_addc_co_u32_e32 v29, vcc, 0, v9, vcc
	v_add_co_u32_e32 v32, vcc, s82, v8
	s_mov_b32 s5, 0x100000
	s_nop 0
	v_addc_co_u32_e32 v33, vcc, 0, v9, vcc
	s_nop 0
	s_nop 0
	s_nop 0
	v_add_co_u32_e32 v36, vcc, s5, v8
	s_mov_b32 s5, 0x140000
	s_nop 0
	v_addc_co_u32_e32 v37, vcc, 0, v9, vcc
	v_add_co_u32_e32 v40, vcc, s5, v8
	s_mov_b32 s5, 0x180000
	s_nop 0
	v_addc_co_u32_e32 v41, vcc, 0, v9, vcc
	s_nop 0
	s_nop 0
	s_nop 0
	v_add_co_u32_e32 v44, vcc, s5, v8
	s_mov_b32 s5, 0x1c0000
	s_nop 0
	v_addc_co_u32_e32 v45, vcc, 0, v9, vcc
	v_add_co_u32_e32 v48, vcc, s5, v8
	s_mov_b32 s5, 0x200000
	s_nop 0
	v_addc_co_u32_e32 v49, vcc, 0, v9, vcc
	s_nop 0
	s_nop 0
	s_nop 0
	v_add_co_u32_e32 v52, vcc, s5, v8
	s_mov_b32 s5, 0x240000
	s_nop 0
	v_addc_co_u32_e32 v53, vcc, 0, v9, vcc
	v_add_co_u32_e32 v56, vcc, s5, v8
	s_mov_b32 s5, 0x280000
	s_nop 0
	v_addc_co_u32_e32 v57, vcc, 0, v9, vcc
	s_nop 0
	s_nop 0
	s_nop 0
	v_add_co_u32_e32 v60, vcc, s5, v8
	s_mov_b32 s5, 0x2c0000
	s_nop 0
	v_addc_co_u32_e32 v61, vcc, 0, v9, vcc
	v_add_co_u32_e32 v64, vcc, s5, v8
	s_mov_b32 s5, 0x300000
	s_nop 0
	v_addc_co_u32_e32 v65, vcc, 0, v9, vcc
	s_nop 0
	s_nop 0
	s_nop 0
	v_add_co_u32_e32 v68, vcc, s5, v8
	s_mov_b32 s5, 0x340000
	s_nop 0
	v_addc_co_u32_e32 v69, vcc, 0, v9, vcc
	s_nop 0
	v_add_co_u32_e32 v72, vcc, s5, v8
	s_mov_b32 s5, 0x380000
	s_nop 0
	v_addc_co_u32_e32 v73, vcc, 0, v9, vcc
	s_nop 0
	v_add_co_u32_e32 v76, vcc, s5, v8
	s_mov_b32 s5, 0x3c0000
	s_nop 0
	v_addc_co_u32_e32 v77, vcc, 0, v9, vcc
	s_nop 0
	v_add_co_u32_e32 v8, vcc, s5, v8
	s_load_dwordx2 s[6:7], s[6:7], 0xa0
	s_nop 0
	v_addc_co_u32_e32 v9, vcc, 0, v9, vcc
	s_nop 0
	v_add_u32_e32 v8, 0x410, v5
	s_cselect_b32 s86, 1, 0
	s_cmpk_lg_i32 s51, 0
	s_cbranch_scc1 .Lcv_w8_b
	s_waitcnt vmcnt(0)

.Lcv_nopf_b:
	s_cmp_lg_u32 s86, 0
	ds_write2_b32 v5, v20, v21 offset1:1
	ds_write2_b32 v5, v22, v23 offset0:2 offset1:3
	ds_write2_b32 v8, v24, v25 offset1:1
	v_add_u32_e32 v8, 0x418, v5
	ds_write2_b32 v8, v26, v27 offset1:1
	v_add_u32_e32 v8, 0x820, v5
	s_add_i32 s5, s48, s51
	s_ashr_i32 s4, s4, 8
	s_add_i32 s8, s5, 0xfffc0000
	ds_write2_b32 v8, v28, v29 offset1:1
	v_add_u32_e32 v8, 0x828, v5
	ds_write2_b32 v8, v30, v31 offset1:1
	v_add_u32_e32 v8, 0xc30, v5
	ds_write2_b32 v8, v32, v33 offset1:1
	v_add_u32_e32 v8, 0xc38, v5
	ds_write2_b32 v8, v34, v35 offset1:1
	v_add_u32_e32 v8, 0x1040, v5
	s_ashr_i32 s5, s4, 31
	s_lshl_b64 s[4:5], s[4:5], 21
	s_lshl_b32 s9, s16, 15
	ds_write2_b32 v8, v36, v37 offset1:1
	v_add_u32_e32 v8, 0x1048, v5
	ds_write2_b32 v8, v38, v39 offset1:1
	v_add_u32_e32 v8, 0x1450, v5
	ds_write2_b32 v8, v40, v41 offset1:1
	v_add_u32_e32 v8, 0x1458, v5
	ds_write2_b32 v8, v42, v43 offset1:1
	v_add_u32_e32 v8, 0x1860, v5
	v_add_u32_e32 v42, 0x400, v10
	s_waitcnt lgkmcnt(0)
	s_add_u32 s4, s6, s4
	s_addc_u32 s5, s7, s5
	ds_write2_b32 v8, v44, v45 offset1:1
	v_add_u32_e32 v8, 0x1868, v5
	ds_write2_b32 v8, v46, v47 offset1:1
	v_add_u32_e32 v8, 0x1c70, v5
	ds_write2_b32 v8, v48, v49 offset1:1
	v_add_u32_e32 v8, 0x1c78, v5
	ds_write2_b32 v8, v50, v51 offset1:1
	v_add_u32_e32 v8, 0x2080, v5
	s_add_u32 s6, s4, s9
	s_addc_u32 s7, s5, 0
	s_and_b32 s4, s8, 0xc0
	ds_write2_b32 v8, v52, v53 offset1:1
	v_add_u32_e32 v8, 0x2088, v5
	ds_write2_b32 v8, v54, v55 offset1:1
	v_add_u32_e32 v8, 0x2490, v5
	ds_write2_b32 v8, v56, v57 offset1:1
	v_add_u32_e32 v8, 0x2498, v5
	ds_write2_b32 v8, v58, v59 offset1:1
	v_add_u32_e32 v8, 0x28a0, v5
	v_mov_b32_e32 v9, v2
	v_mov_b32_e32 v41, v2
	ds_write2_b32 v8, v60, v61 offset1:1
	v_add_u32_e32 v8, 0x28a8, v5
	ds_write2_b32 v8, v62, v63 offset1:1
	v_add_u32_e32 v8, 0x2cb0, v5
	ds_write2_b32 v8, v64, v65 offset1:1
	v_add_u32_e32 v8, 0x2cb8, v5
	ds_write2_b32 v8, v66, v67 offset1:1
	v_add_u32_e32 v8, 0x30c0, v5
	ds_write2_b32 v8, v68, v69 offset1:1
	v_add_u32_e32 v8, 0x30c8, v5
	ds_write2_b32 v8, v70, v71 offset1:1
	v_add_u32_e32 v8, 0x34d0, v5
	ds_write2_b32 v8, v72, v73 offset1:1
	v_add_u32_e32 v8, 0x34d8, v5
	ds_write2_b32 v8, v74, v75 offset1:1
	v_add_u32_e32 v8, 0x38e0, v5
	ds_write2_b32 v8, v76, v77 offset1:1
	v_add_u32_e32 v8, 0x38e8, v5
	ds_write2_b32 v8, v78, v79 offset1:1
	v_add_u32_e32 v8, 0x3cf0, v5
	ds_write2_b32 v8, v80, v81 offset1:1
	v_add_u32_e32 v8, 0x3cf8, v5
	ds_write2_b32 v8, v82, v83 offset1:1
	s_waitcnt lgkmcnt(0)
	ds_read2_b32 v[24:25], v10 offset1:8
	ds_read2_b32 v[26:27], v10 offset0:65 offset1:73
	ds_read2_b32 v[28:29], v10 offset0:130 offset1:138
	ds_read2_b32 v[30:31], v10 offset0:195 offset1:203
	ds_read2_b32 v[32:33], v42 offset0:4 offset1:12
	s_waitcnt lgkmcnt(4)
	v_bfe_u32 v19, v24, 16, 1
	v_add3_u32 v19, v24, v19, s87
	s_waitcnt lgkmcnt(3)
	v_bfe_u32 v20, v26, 16, 1
	v_lshrrev_b32_e32 v19, 16, v19
	v_add3_u32 v20, v26, v20, s87
	ds_read2_b32 v[34:35], v42 offset0:69 offset1:77
	v_and_or_b32 v20, v20, s90, v19
	s_waitcnt lgkmcnt(3)
	v_bfe_u32 v19, v28, 16, 1
	v_add3_u32 v19, v28, v19, s87
	s_waitcnt lgkmcnt(2)
	v_bfe_u32 v21, v30, 16, 1
	ds_read2_b32 v[36:37], v42 offset0:134 offset1:142
	v_lshrrev_b32_e32 v19, 16, v19
	v_add3_u32 v21, v30, v21, s87
	ds_read2_b32 v[38:39], v42 offset0:199 offset1:207
	v_and_or_b32 v21, v21, s90, v19
	s_waitcnt lgkmcnt(3)
	v_bfe_u32 v19, v32, 16, 1
	v_add3_u32 v19, v32, v19, s87
	s_waitcnt lgkmcnt(2)
	v_bfe_u32 v22, v34, 16, 1
	v_lshrrev_b32_e32 v19, 16, v19
	v_add3_u32 v22, v34, v22, s87
	v_and_or_b32 v22, v22, s90, v19
	s_waitcnt lgkmcnt(1)
	v_bfe_u32 v19, v36, 16, 1
	v_add3_u32 v19, v36, v19, s87
	s_waitcnt lgkmcnt(0)
	v_bfe_u32 v23, v38, 16, 1
	v_lshlrev_b32_e32 v8, 1, v6
	v_lshrrev_b32_e32 v19, 16, v19
	v_add3_u32 v23, v38, v23, s87
	v_lshl_add_u64 v[8:9], s[6:7], 0, v[8:9]
	s_mov_b64 s[6:7], 0x8400000
	v_and_or_b32 v23, v23, s90, v19
	v_or_b32_e32 v19, s4, v7
	v_lshl_add_u64 v[8:9], v[8:9], 0, s[6:7]
	v_lshlrev_b32_e32 v40, 7, v19
	v_lshl_add_u64 v[40:41], v[8:9], 0, v[40:41]
	v_bfe_u32 v19, v25, 16, 1
	global_store_dwordx4 v[40:41], v[20:23], off
	v_add3_u32 v19, v25, v19, s87
	v_lshrrev_b32_e32 v19, 16, v19
	v_bfe_u32 v20, v27, 16, 1
	v_add3_u32 v20, v27, v20, s87
	v_and_or_b32 v20, v20, s90, v19
	v_bfe_u32 v19, v29, 16, 1
	v_add3_u32 v19, v29, v19, s87
	v_bfe_u32 v21, v31, 16, 1
	v_lshrrev_b32_e32 v19, 16, v19
	v_add3_u32 v21, v31, v21, s87
	v_and_or_b32 v21, v21, s90, v19
	v_bfe_u32 v19, v33, 16, 1
	v_add3_u32 v19, v33, v19, s87
	v_bfe_u32 v22, v35, 16, 1
	v_lshrrev_b32_e32 v19, 16, v19
	v_add3_u32 v22, v35, v22, s87
	v_and_or_b32 v22, v22, s90, v19
	v_bfe_u32 v19, v37, 16, 1
	v_add3_u32 v19, v37, v19, s87
	v_bfe_u32 v23, v39, 16, 1
	v_lshrrev_b32_e32 v19, 16, v19
	v_add3_u32 v23, v39, v23, s87
	v_and_or_b32 v23, v23, s90, v19
	v_or_b32_e32 v19, s4, v11
	v_lshlrev_b32_e32 v24, 7, v19
	v_mov_b32_e32 v25, v2
	ds_read2_b32 v[26:27], v10 offset0:16 offset1:24
	v_lshl_add_u64 v[24:25], v[8:9], 0, v[24:25]
	global_store_dwordx4 v[24:25], v[20:23], off
	ds_read2_b32 v[24:25], v10 offset0:81 offset1:89
	ds_read2_b32 v[28:29], v10 offset0:146 offset1:154
	ds_read2_b32 v[30:31], v10 offset0:211 offset1:219
	s_waitcnt lgkmcnt(3)
	v_bfe_u32 v19, v26, 16, 1
	v_add3_u32 v19, v26, v19, s87
	s_waitcnt lgkmcnt(2)
	v_bfe_u32 v20, v24, 16, 1
	ds_read2_b32 v[32:33], v42 offset0:20 offset1:28
	v_lshrrev_b32_e32 v19, 16, v19
	v_add3_u32 v20, v24, v20, s87
	ds_read2_b32 v[34:35], v42 offset0:85 offset1:93
	v_and_or_b32 v20, v20, s90, v19
	s_waitcnt lgkmcnt(3)
	v_bfe_u32 v19, v28, 16, 1
	v_add3_u32 v19, v28, v19, s87
	s_waitcnt lgkmcnt(2)
	v_bfe_u32 v21, v30, 16, 1
	ds_read2_b32 v[36:37], v42 offset0:150 offset1:158
	v_lshrrev_b32_e32 v19, 16, v19
	v_add3_u32 v21, v30, v21, s87
	ds_read2_b32 v[38:39], v42 offset0:215 offset1:223
	v_and_or_b32 v21, v21, s90, v19
	s_waitcnt lgkmcnt(3)
	v_bfe_u32 v19, v32, 16, 1
	v_add3_u32 v19, v32, v19, s87
	s_waitcnt lgkmcnt(2)
	v_bfe_u32 v22, v34, 16, 1
	v_lshrrev_b32_e32 v19, 16, v19
	v_add3_u32 v22, v34, v22, s87
	v_and_or_b32 v22, v22, s90, v19
	s_waitcnt lgkmcnt(1)
	v_bfe_u32 v19, v36, 16, 1
	v_add3_u32 v19, v36, v19, s87
	s_waitcnt lgkmcnt(0)
	v_bfe_u32 v23, v38, 16, 1
	v_lshrrev_b32_e32 v19, 16, v19
	v_add3_u32 v23, v38, v23, s87
	v_and_or_b32 v23, v23, s90, v19
	v_or_b32_e32 v19, s4, v12
	v_lshlrev_b32_e32 v40, 7, v19
	v_mov_b32_e32 v41, v2
	v_lshl_add_u64 v[40:41], v[8:9], 0, v[40:41]
	v_bfe_u32 v19, v27, 16, 1
	global_store_dwordx4 v[40:41], v[20:23], off
	v_add3_u32 v19, v27, v19, s87
	v_lshrrev_b32_e32 v19, 16, v19
	v_bfe_u32 v20, v25, 16, 1
	v_add3_u32 v20, v25, v20, s87
	v_and_or_b32 v20, v20, s90, v19
	v_bfe_u32 v19, v29, 16, 1
	v_add3_u32 v19, v29, v19, s87
	v_bfe_u32 v21, v31, 16, 1
	v_lshrrev_b32_e32 v19, 16, v19
	v_add3_u32 v21, v31, v21, s87
	v_and_or_b32 v21, v21, s90, v19
	v_bfe_u32 v19, v33, 16, 1
	v_add3_u32 v19, v33, v19, s87
	v_bfe_u32 v22, v35, 16, 1
	v_lshrrev_b32_e32 v19, 16, v19
	v_add3_u32 v22, v35, v22, s87
	v_and_or_b32 v22, v22, s90, v19
	v_bfe_u32 v19, v37, 16, 1
	v_add3_u32 v19, v37, v19, s87
	v_bfe_u32 v23, v39, 16, 1
	v_lshrrev_b32_e32 v19, 16, v19
	v_add3_u32 v23, v39, v23, s87
	v_and_or_b32 v23, v23, s90, v19
	v_or_b32_e32 v19, s4, v13
	v_lshlrev_b32_e32 v24, 7, v19
	v_mov_b32_e32 v25, v2
	ds_read2_b32 v[26:27], v10 offset0:32 offset1:40
	v_lshl_add_u64 v[24:25], v[8:9], 0, v[24:25]
	global_store_dwordx4 v[24:25], v[20:23], off
	ds_read2_b32 v[24:25], v10 offset0:97 offset1:105
	ds_read2_b32 v[28:29], v10 offset0:162 offset1:170
	ds_read2_b32 v[30:31], v10 offset0:227 offset1:235
	s_waitcnt lgkmcnt(3)
	v_bfe_u32 v19, v26, 16, 1
	v_add3_u32 v19, v26, v19, s87
	s_waitcnt lgkmcnt(2)
	v_bfe_u32 v20, v24, 16, 1
	ds_read2_b32 v[32:33], v42 offset0:36 offset1:44
	v_lshrrev_b32_e32 v19, 16, v19
	v_add3_u32 v20, v24, v20, s87
	ds_read2_b32 v[34:35], v42 offset0:101 offset1:109
	v_and_or_b32 v20, v20, s90, v19
	s_waitcnt lgkmcnt(3)
	v_bfe_u32 v19, v28, 16, 1
	v_add3_u32 v19, v28, v19, s87
	s_waitcnt lgkmcnt(2)
	v_bfe_u32 v21, v30, 16, 1
	ds_read2_b32 v[36:37], v42 offset0:166 offset1:174
	v_lshrrev_b32_e32 v19, 16, v19
	v_add3_u32 v21, v30, v21, s87
	ds_read2_b32 v[38:39], v42 offset0:231 offset1:239
	v_and_or_b32 v21, v21, s90, v19
	s_waitcnt lgkmcnt(3)
	v_bfe_u32 v19, v32, 16, 1
	v_add3_u32 v19, v32, v19, s87
	s_waitcnt lgkmcnt(2)
	v_bfe_u32 v22, v34, 16, 1
	v_lshrrev_b32_e32 v19, 16, v19
	v_add3_u32 v22, v34, v22, s87
	v_and_or_b32 v22, v22, s90, v19
	s_waitcnt lgkmcnt(1)
	v_bfe_u32 v19, v36, 16, 1
	v_add3_u32 v19, v36, v19, s87
	s_waitcnt lgkmcnt(0)
	v_bfe_u32 v23, v38, 16, 1
	v_lshrrev_b32_e32 v19, 16, v19
	v_add3_u32 v23, v38, v23, s87
	v_and_or_b32 v23, v23, s90, v19
	v_or_b32_e32 v19, s4, v14
	v_lshlrev_b32_e32 v40, 7, v19
	v_mov_b32_e32 v41, v2
	v_lshl_add_u64 v[40:41], v[8:9], 0, v[40:41]
	v_bfe_u32 v19, v27, 16, 1
	global_store_dwordx4 v[40:41], v[20:23], off
	v_add3_u32 v19, v27, v19, s87
	v_lshrrev_b32_e32 v19, 16, v19
	v_bfe_u32 v20, v25, 16, 1
	v_add3_u32 v20, v25, v20, s87
	v_and_or_b32 v20, v20, s90, v19
	v_bfe_u32 v19, v29, 16, 1
	v_add3_u32 v19, v29, v19, s87
	v_bfe_u32 v21, v31, 16, 1
	v_lshrrev_b32_e32 v19, 16, v19
	v_add3_u32 v21, v31, v21, s87
	v_and_or_b32 v21, v21, s90, v19
	v_bfe_u32 v19, v33, 16, 1
	v_add3_u32 v19, v33, v19, s87
	v_bfe_u32 v22, v35, 16, 1
	v_lshrrev_b32_e32 v19, 16, v19
	v_add3_u32 v22, v35, v22, s87
	v_and_or_b32 v22, v22, s90, v19
	v_bfe_u32 v19, v37, 16, 1
	v_add3_u32 v19, v37, v19, s87
	v_bfe_u32 v23, v39, 16, 1
	v_lshrrev_b32_e32 v19, 16, v19
	v_add3_u32 v23, v39, v23, s87
	v_and_or_b32 v23, v23, s90, v19
	v_or_b32_e32 v19, s4, v15
	v_lshlrev_b32_e32 v24, 7, v19
	v_mov_b32_e32 v25, v2
	ds_read2_b32 v[26:27], v10 offset0:48 offset1:56
	v_lshl_add_u64 v[24:25], v[8:9], 0, v[24:25]
	global_store_dwordx4 v[24:25], v[20:23], off
	ds_read2_b32 v[24:25], v10 offset0:113 offset1:121
	ds_read2_b32 v[28:29], v10 offset0:178 offset1:186
	ds_read2_b32 v[30:31], v10 offset0:243 offset1:251
	s_waitcnt lgkmcnt(3)
	v_bfe_u32 v19, v26, 16, 1
	v_add3_u32 v19, v26, v19, s87
	s_waitcnt lgkmcnt(2)
	v_bfe_u32 v20, v24, 16, 1
	ds_read2_b32 v[32:33], v42 offset0:52 offset1:60
	v_lshrrev_b32_e32 v19, 16, v19
	v_add3_u32 v20, v24, v20, s87
	ds_read2_b32 v[34:35], v42 offset0:117 offset1:125
	v_and_or_b32 v20, v20, s90, v19
	s_waitcnt lgkmcnt(3)
	v_bfe_u32 v19, v28, 16, 1
	v_add3_u32 v19, v28, v19, s87
	s_waitcnt lgkmcnt(2)
	v_bfe_u32 v21, v30, 16, 1
	ds_read2_b32 v[36:37], v42 offset0:182 offset1:190
	v_lshrrev_b32_e32 v19, 16, v19
	v_add3_u32 v21, v30, v21, s87
	ds_read2_b32 v[38:39], v42 offset0:247 offset1:255
	v_and_or_b32 v21, v21, s90, v19
	s_waitcnt lgkmcnt(3)
	v_bfe_u32 v19, v32, 16, 1
	v_add3_u32 v19, v32, v19, s87
	s_waitcnt lgkmcnt(2)
	v_bfe_u32 v22, v34, 16, 1
	v_lshrrev_b32_e32 v19, 16, v19
	v_add3_u32 v22, v34, v22, s87
	v_and_or_b32 v22, v22, s90, v19
	s_waitcnt lgkmcnt(1)
	v_bfe_u32 v19, v36, 16, 1
	v_add3_u32 v19, v36, v19, s87
	s_waitcnt lgkmcnt(0)
	v_bfe_u32 v23, v38, 16, 1
	v_lshrrev_b32_e32 v19, 16, v19
	v_add3_u32 v23, v38, v23, s87
	v_and_or_b32 v23, v23, s90, v19
	v_or_b32_e32 v19, s4, v16
	v_lshlrev_b32_e32 v40, 7, v19
	v_mov_b32_e32 v41, v2
	v_lshl_add_u64 v[40:41], v[8:9], 0, v[40:41]
	v_bfe_u32 v19, v27, 16, 1
	global_store_dwordx4 v[40:41], v[20:23], off
	v_add3_u32 v19, v27, v19, s87
	v_lshrrev_b32_e32 v19, 16, v19
	v_bfe_u32 v20, v25, 16, 1
	v_add3_u32 v20, v25, v20, s87
	v_and_or_b32 v20, v20, s90, v19
	v_bfe_u32 v19, v29, 16, 1
	v_add3_u32 v19, v29, v19, s87
	v_bfe_u32 v21, v31, 16, 1
	v_lshrrev_b32_e32 v19, 16, v19
	v_add3_u32 v21, v31, v21, s87
	v_and_or_b32 v21, v21, s90, v19
	v_bfe_u32 v19, v33, 16, 1
	v_add3_u32 v19, v33, v19, s87
	v_bfe_u32 v22, v35, 16, 1
	v_lshrrev_b32_e32 v19, 16, v19
	v_add3_u32 v22, v35, v22, s87
	v_and_or_b32 v22, v22, s90, v19
	v_bfe_u32 v19, v37, 16, 1
	v_add3_u32 v19, v37, v19, s87
	v_bfe_u32 v23, v39, 16, 1
	v_lshrrev_b32_e32 v19, 16, v19
	v_add3_u32 v23, v39, v23, s87
	v_and_or_b32 v23, v23, s90, v19
	v_or_b32_e32 v19, s4, v17
	v_lshlrev_b32_e32 v24, 7, v19
	v_mov_b32_e32 v25, v2
	v_lshl_add_u64 v[8:9], v[8:9], 0, v[24:25]
	global_store_dwordx4 v[8:9], v[20:23], off
	s_waitcnt lgkmcnt(0)

.LBB0_366:
	s_andn2_b64 vcc, exec, s[4:5]
	s_cbranch_vccnz .LBB0_359
	s_mov_b64 s[4:5], s[0:1]
	s_load_dwordx2 s[16:17], s[4:5], 0x70
	s_ashr_i32 s4, s2, 31
	s_lshr_b32 s4, s4, 26
	s_add_i32 s5, s2, s4
	s_ashr_i32 s4, s5, 6
	s_andn2_b32 s5, s5, 63
	v_or_b32_e32 v8, s5, v3
	s_add_i32 s12, s48, s51
	s_lshl_b32 s6, s4, 12
	v_ashrrev_i32_e32 v9, 31, v8
	s_sub_i32 s6, s12, s6
	v_lshlrev_b64 v[8:9], 14, v[8:9]
	s_waitcnt lgkmcnt(0)
	v_lshl_add_u64 v[8:9], s[16:17], 0, v[8:9]
	s_ashr_i32 s7, s6, 31
	v_lshl_add_u64 v[8:9], s[6:7], 2, v[8:9]
	v_lshlrev_b32_e32 v20, 2, v4
	v_mov_b32_e32 v21, v2
	v_lshl_add_u64 v[8:9], v[8:9], 0, v[20:21]
	v_add_co_u32_e32 v24, vcc, s3, v8
	s_mov_b64 s[8:9], s[0:1]
	s_nop 0
	v_addc_co_u32_e32 v25, vcc, 0, v9, vcc
	v_add_co_u32_e32 v28, vcc, s45, v8
	s_nop 0
	s_nop 0
	s_nop 0
	v_addc_co_u32_e32 v29, vcc, 0, v9, vcc
	v_add_co_u32_e32 v32, vcc, s47, v8
	s_ashr_i32 s6, s6, 8
	s_nop 0
	v_addc_co_u32_e32 v33, vcc, 0, v9, vcc
	s_nop 0
	s_nop 0
	s_nop 0
	v_add_co_u32_e32 v36, vcc, s10, v8
	s_ashr_i32 s7, s6, 31
	s_nop 0
	v_addc_co_u32_e32 v37, vcc, 0, v9, vcc
	v_add_co_u32_e32 v40, vcc, s11, v8
	s_ashr_i32 s5, s4, 31
	s_nop 0
	v_addc_co_u32_e32 v41, vcc, 0, v9, vcc
	s_nop 0
	s_nop 0
	s_nop 0
	v_add_co_u32_e32 v44, vcc, s80, v8
	s_lshl_b64 s[6:7], s[6:7], 21
	s_nop 0
	v_addc_co_u32_e32 v45, vcc, 0, v9, vcc
	v_add_co_u32_e32 v48, vcc, s41, v8
	s_lshl_b64 s[4:5], s[4:5], 15
	s_nop 0
	v_addc_co_u32_e32 v49, vcc, 0, v9, vcc
	s_nop 0
	s_nop 0
	s_nop 0
	v_add_co_u32_e32 v52, vcc, s43, v8
	s_nop 1
	v_addc_co_u32_e32 v53, vcc, 0, v9, vcc
	v_add_co_u32_e32 v56, vcc, s78, v8
	s_nop 1
	v_addc_co_u32_e32 v57, vcc, 0, v9, vcc
	s_nop 0
	s_nop 0
	s_nop 0
	v_add_co_u32_e32 v60, vcc, s79, v8
	s_nop 1
	v_addc_co_u32_e32 v61, vcc, 0, v9, vcc
	v_add_co_u32_e32 v64, vcc, s81, v8
	s_nop 1
	v_addc_co_u32_e32 v65, vcc, 0, v9, vcc
	s_nop 0
	s_nop 0
	s_nop 0
	v_add_co_u32_e32 v68, vcc, s82, v8
	s_load_dwordx2 s[8:9], s[8:9], 0xa0
	s_nop 0
	v_addc_co_u32_e32 v69, vcc, 0, v9, vcc
	s_nop 0
	v_add_co_u32_e32 v72, vcc, s83, v8
	s_waitcnt lgkmcnt(0)
	s_add_u32 s6, s8, s6
	v_addc_co_u32_e32 v73, vcc, 0, v9, vcc
	s_nop 0
	v_add_co_u32_e32 v76, vcc, s84, v8
	s_addc_u32 s7, s9, s7
	s_nop 0
	v_addc_co_u32_e32 v77, vcc, 0, v9, vcc
	s_nop 0
	v_add_co_u32_e32 v8, vcc, s86, v8
	s_add_u32 s6, s6, s4
	s_nop 0
	v_addc_co_u32_e32 v9, vcc, 0, v9, vcc
	s_nop 0
	v_add_u32_e32 v8, 0x410, v5
	s_cselect_b32 s86, 1, 0
	s_cmpk_lg_i32 s51, 0
	s_cbranch_scc1 .Lcv_w8_c
	s_waitcnt vmcnt(0)

.Lcv_nopf_c:
	s_cmp_lg_u32 s86, 0
	ds_write2_b32 v5, v20, v21 offset1:1
	ds_write2_b32 v5, v22, v23 offset0:2 offset1:3
	ds_write2_b32 v8, v24, v25 offset1:1
	v_add_u32_e32 v8, 0x418, v5
	ds_write2_b32 v8, v26, v27 offset1:1
	v_add_u32_e32 v8, 0x820, v5
	s_addc_u32 s7, s7, s5
	s_and_b32 s4, s12, 0xc0
	v_mov_b32_e32 v9, v2
	ds_write2_b32 v8, v28, v29 offset1:1
	v_add_u32_e32 v8, 0x828, v5
	ds_write2_b32 v8, v30, v31 offset1:1
	v_add_u32_e32 v8, 0xc30, v5
	ds_write2_b32 v8, v32, v33 offset1:1
	v_add_u32_e32 v8, 0xc38, v5
	ds_write2_b32 v8, v34, v35 offset1:1
	v_add_u32_e32 v8, 0x1040, v5
	ds_write2_b32 v8, v36, v37 offset1:1
	v_add_u32_e32 v8, 0x1048, v5
	ds_write2_b32 v8, v38, v39 offset1:1
	v_add_u32_e32 v8, 0x1450, v5
	ds_write2_b32 v8, v40, v41 offset1:1
	v_add_u32_e32 v8, 0x1458, v5
	ds_write2_b32 v8, v42, v43 offset1:1
	v_add_u32_e32 v8, 0x1860, v5
	v_add_u32_e32 v42, 0x400, v10
	v_mov_b32_e32 v41, v2
	ds_write2_b32 v8, v44, v45 offset1:1
	v_add_u32_e32 v8, 0x1868, v5
	ds_write2_b32 v8, v46, v47 offset1:1
	v_add_u32_e32 v8, 0x1c70, v5
	ds_write2_b32 v8, v48, v49 offset1:1
	v_add_u32_e32 v8, 0x1c78, v5
	ds_write2_b32 v8, v50, v51 offset1:1
	v_add_u32_e32 v8, 0x2080, v5
	ds_write2_b32 v8, v52, v53 offset1:1
	v_add_u32_e32 v8, 0x2088, v5
	ds_write2_b32 v8, v54, v55 offset1:1
	v_add_u32_e32 v8, 0x2490, v5
	ds_write2_b32 v8, v56, v57 offset1:1
	v_add_u32_e32 v8, 0x2498, v5
	ds_write2_b32 v8, v58, v59 offset1:1
	v_add_u32_e32 v8, 0x28a0, v5
	ds_write2_b32 v8, v60, v61 offset1:1
	v_add_u32_e32 v8, 0x28a8, v5
	ds_write2_b32 v8, v62, v63 offset1:1
	v_add_u32_e32 v8, 0x2cb0, v5
	ds_write2_b32 v8, v64, v65 offset1:1
	v_add_u32_e32 v8, 0x2cb8, v5
	ds_write2_b32 v8, v66, v67 offset1:1
	v_add_u32_e32 v8, 0x30c0, v5
	ds_write2_b32 v8, v68, v69 offset1:1
	v_add_u32_e32 v8, 0x30c8, v5
	ds_write2_b32 v8, v70, v71 offset1:1
	v_add_u32_e32 v8, 0x34d0, v5
	ds_write2_b32 v8, v72, v73 offset1:1
	v_add_u32_e32 v8, 0x34d8, v5
	ds_write2_b32 v8, v74, v75 offset1:1
	v_add_u32_e32 v8, 0x38e0, v5
	ds_write2_b32 v8, v76, v77 offset1:1
	v_add_u32_e32 v8, 0x38e8, v5
	ds_write2_b32 v8, v78, v79 offset1:1
	v_add_u32_e32 v8, 0x3cf0, v5
	ds_write2_b32 v8, v80, v81 offset1:1
	v_add_u32_e32 v8, 0x3cf8, v5
	ds_write2_b32 v8, v82, v83 offset1:1
	s_waitcnt lgkmcnt(0)
	ds_read2_b32 v[24:25], v10 offset1:8
	ds_read2_b32 v[26:27], v10 offset0:65 offset1:73
	ds_read2_b32 v[28:29], v10 offset0:130 offset1:138
	ds_read2_b32 v[30:31], v10 offset0:195 offset1:203
	ds_read2_b32 v[32:33], v42 offset0:4 offset1:12
	s_waitcnt lgkmcnt(4)
	v_bfe_u32 v19, v24, 16, 1
	v_add3_u32 v19, v24, v19, s87
	s_waitcnt lgkmcnt(3)
	v_bfe_u32 v20, v26, 16, 1
	v_lshrrev_b32_e32 v19, 16, v19
	v_add3_u32 v20, v26, v20, s87
	ds_read2_b32 v[34:35], v42 offset0:69 offset1:77
	v_and_or_b32 v20, v20, s90, v19
	s_waitcnt lgkmcnt(3)
	v_bfe_u32 v19, v28, 16, 1
	v_add3_u32 v19, v28, v19, s87
	s_waitcnt lgkmcnt(2)
	v_bfe_u32 v21, v30, 16, 1
	ds_read2_b32 v[36:37], v42 offset0:134 offset1:142
	v_lshrrev_b32_e32 v19, 16, v19
	v_add3_u32 v21, v30, v21, s87
	ds_read2_b32 v[38:39], v42 offset0:199 offset1:207
	v_and_or_b32 v21, v21, s90, v19
	s_waitcnt lgkmcnt(3)
	v_bfe_u32 v19, v32, 16, 1
	v_add3_u32 v19, v32, v19, s87
	s_waitcnt lgkmcnt(2)
	v_bfe_u32 v22, v34, 16, 1
	v_lshrrev_b32_e32 v19, 16, v19
	v_add3_u32 v22, v34, v22, s87
	v_and_or_b32 v22, v22, s90, v19
	s_waitcnt lgkmcnt(1)
	v_bfe_u32 v19, v36, 16, 1
	v_add3_u32 v19, v36, v19, s87
	s_waitcnt lgkmcnt(0)
	v_bfe_u32 v23, v38, 16, 1
	v_lshlrev_b32_e32 v8, 1, v6
	v_lshrrev_b32_e32 v19, 16, v19
	v_add3_u32 v23, v38, v23, s87
	v_lshl_add_u64 v[8:9], s[6:7], 0, v[8:9]
	s_mov_b64 s[6:7], 0x6400000
	v_and_or_b32 v23, v23, s90, v19
	v_or_b32_e32 v19, s4, v7
	v_lshl_add_u64 v[8:9], v[8:9], 0, s[6:7]
	v_lshlrev_b32_e32 v40, 7, v19
	v_lshl_add_u64 v[40:41], v[8:9], 0, v[40:41]
	v_bfe_u32 v19, v25, 16, 1
	global_store_dwordx4 v[40:41], v[20:23], off
	v_add3_u32 v19, v25, v19, s87
	v_lshrrev_b32_e32 v19, 16, v19
	v_bfe_u32 v20, v27, 16, 1
	v_add3_u32 v20, v27, v20, s87
	v_and_or_b32 v20, v20, s90, v19
	v_bfe_u32 v19, v29, 16, 1
	v_add3_u32 v19, v29, v19, s87
	v_bfe_u32 v21, v31, 16, 1
	v_lshrrev_b32_e32 v19, 16, v19
	v_add3_u32 v21, v31, v21, s87
	v_and_or_b32 v21, v21, s90, v19
	v_bfe_u32 v19, v33, 16, 1
	v_add3_u32 v19, v33, v19, s87
	v_bfe_u32 v22, v35, 16, 1
	v_lshrrev_b32_e32 v19, 16, v19
	v_add3_u32 v22, v35, v22, s87
	v_and_or_b32 v22, v22, s90, v19
	v_bfe_u32 v19, v37, 16, 1
	v_add3_u32 v19, v37, v19, s87
	v_bfe_u32 v23, v39, 16, 1
	v_lshrrev_b32_e32 v19, 16, v19
	v_add3_u32 v23, v39, v23, s87
	v_and_or_b32 v23, v23, s90, v19
	v_or_b32_e32 v19, s4, v11
	v_lshlrev_b32_e32 v24, 7, v19
	v_mov_b32_e32 v25, v2
	ds_read2_b32 v[26:27], v10 offset0:16 offset1:24
	v_lshl_add_u64 v[24:25], v[8:9], 0, v[24:25]
	global_store_dwordx4 v[24:25], v[20:23], off
	ds_read2_b32 v[24:25], v10 offset0:81 offset1:89
	ds_read2_b32 v[28:29], v10 offset0:146 offset1:154
	ds_read2_b32 v[30:31], v10 offset0:211 offset1:219
	s_waitcnt lgkmcnt(3)
	v_bfe_u32 v19, v26, 16, 1
	v_add3_u32 v19, v26, v19, s87
	s_waitcnt lgkmcnt(2)
	v_bfe_u32 v20, v24, 16, 1
	ds_read2_b32 v[32:33], v42 offset0:20 offset1:28
	v_lshrrev_b32_e32 v19, 16, v19
	v_add3_u32 v20, v24, v20, s87
	ds_read2_b32 v[34:35], v42 offset0:85 offset1:93
	v_and_or_b32 v20, v20, s90, v19
	s_waitcnt lgkmcnt(3)
	v_bfe_u32 v19, v28, 16, 1
	v_add3_u32 v19, v28, v19, s87
	s_waitcnt lgkmcnt(2)
	v_bfe_u32 v21, v30, 16, 1
	ds_read2_b32 v[36:37], v42 offset0:150 offset1:158
	v_lshrrev_b32_e32 v19, 16, v19
	v_add3_u32 v21, v30, v21, s87
	ds_read2_b32 v[38:39], v42 offset0:215 offset1:223
	v_and_or_b32 v21, v21, s90, v19
	s_waitcnt lgkmcnt(3)
	v_bfe_u32 v19, v32, 16, 1
	v_add3_u32 v19, v32, v19, s87
	s_waitcnt lgkmcnt(2)
	v_bfe_u32 v22, v34, 16, 1
	v_lshrrev_b32_e32 v19, 16, v19
	v_add3_u32 v22, v34, v22, s87
	v_and_or_b32 v22, v22, s90, v19
	s_waitcnt lgkmcnt(1)
	v_bfe_u32 v19, v36, 16, 1
	v_add3_u32 v19, v36, v19, s87
	s_waitcnt lgkmcnt(0)
	v_bfe_u32 v23, v38, 16, 1
	v_lshrrev_b32_e32 v19, 16, v19
	v_add3_u32 v23, v38, v23, s87
	v_and_or_b32 v23, v23, s90, v19
	v_or_b32_e32 v19, s4, v12
	v_lshlrev_b32_e32 v40, 7, v19
	v_mov_b32_e32 v41, v2
	v_lshl_add_u64 v[40:41], v[8:9], 0, v[40:41]
	v_bfe_u32 v19, v27, 16, 1
	global_store_dwordx4 v[40:41], v[20:23], off
	v_add3_u32 v19, v27, v19, s87
	v_lshrrev_b32_e32 v19, 16, v19
	v_bfe_u32 v20, v25, 16, 1
	v_add3_u32 v20, v25, v20, s87
	v_and_or_b32 v20, v20, s90, v19
	v_bfe_u32 v19, v29, 16, 1
	v_add3_u32 v19, v29, v19, s87
	v_bfe_u32 v21, v31, 16, 1
	v_lshrrev_b32_e32 v19, 16, v19
	v_add3_u32 v21, v31, v21, s87
	v_and_or_b32 v21, v21, s90, v19
	v_bfe_u32 v19, v33, 16, 1
	v_add3_u32 v19, v33, v19, s87
	v_bfe_u32 v22, v35, 16, 1
	v_lshrrev_b32_e32 v19, 16, v19
	v_add3_u32 v22, v35, v22, s87
	v_and_or_b32 v22, v22, s90, v19
	v_bfe_u32 v19, v37, 16, 1
	v_add3_u32 v19, v37, v19, s87
	v_bfe_u32 v23, v39, 16, 1
	v_lshrrev_b32_e32 v19, 16, v19
	v_add3_u32 v23, v39, v23, s87
	v_and_or_b32 v23, v23, s90, v19
	v_or_b32_e32 v19, s4, v13
	v_lshlrev_b32_e32 v24, 7, v19
	v_mov_b32_e32 v25, v2
	ds_read2_b32 v[26:27], v10 offset0:32 offset1:40
	v_lshl_add_u64 v[24:25], v[8:9], 0, v[24:25]
	global_store_dwordx4 v[24:25], v[20:23], off
	ds_read2_b32 v[24:25], v10 offset0:97 offset1:105
	ds_read2_b32 v[28:29], v10 offset0:162 offset1:170
	ds_read2_b32 v[30:31], v10 offset0:227 offset1:235
	s_waitcnt lgkmcnt(3)
	v_bfe_u32 v19, v26, 16, 1
	v_add3_u32 v19, v26, v19, s87
	s_waitcnt lgkmcnt(2)
	v_bfe_u32 v20, v24, 16, 1
	ds_read2_b32 v[32:33], v42 offset0:36 offset1:44
	v_lshrrev_b32_e32 v19, 16, v19
	v_add3_u32 v20, v24, v20, s87
	ds_read2_b32 v[34:35], v42 offset0:101 offset1:109
	v_and_or_b32 v20, v20, s90, v19
	s_waitcnt lgkmcnt(3)
	v_bfe_u32 v19, v28, 16, 1
	v_add3_u32 v19, v28, v19, s87
	s_waitcnt lgkmcnt(2)
	v_bfe_u32 v21, v30, 16, 1
	ds_read2_b32 v[36:37], v42 offset0:166 offset1:174
	v_lshrrev_b32_e32 v19, 16, v19
	v_add3_u32 v21, v30, v21, s87
	ds_read2_b32 v[38:39], v42 offset0:231 offset1:239
	v_and_or_b32 v21, v21, s90, v19
	s_waitcnt lgkmcnt(3)
	v_bfe_u32 v19, v32, 16, 1
	v_add3_u32 v19, v32, v19, s87
	s_waitcnt lgkmcnt(2)
	v_bfe_u32 v22, v34, 16, 1
	v_lshrrev_b32_e32 v19, 16, v19
	v_add3_u32 v22, v34, v22, s87
	v_and_or_b32 v22, v22, s90, v19
	s_waitcnt lgkmcnt(1)
	v_bfe_u32 v19, v36, 16, 1
	v_add3_u32 v19, v36, v19, s87
	s_waitcnt lgkmcnt(0)
	v_bfe_u32 v23, v38, 16, 1
	v_lshrrev_b32_e32 v19, 16, v19
	v_add3_u32 v23, v38, v23, s87
	v_and_or_b32 v23, v23, s90, v19
	v_or_b32_e32 v19, s4, v14
	v_lshlrev_b32_e32 v40, 7, v19
	v_mov_b32_e32 v41, v2
	v_lshl_add_u64 v[40:41], v[8:9], 0, v[40:41]
	v_bfe_u32 v19, v27, 16, 1
	global_store_dwordx4 v[40:41], v[20:23], off
	v_add3_u32 v19, v27, v19, s87
	v_lshrrev_b32_e32 v19, 16, v19
	v_bfe_u32 v20, v25, 16, 1
	v_add3_u32 v20, v25, v20, s87
	v_and_or_b32 v20, v20, s90, v19
	v_bfe_u32 v19, v29, 16, 1
	v_add3_u32 v19, v29, v19, s87
	v_bfe_u32 v21, v31, 16, 1
	v_lshrrev_b32_e32 v19, 16, v19
	v_add3_u32 v21, v31, v21, s87
	v_and_or_b32 v21, v21, s90, v19
	v_bfe_u32 v19, v33, 16, 1
	v_add3_u32 v19, v33, v19, s87
	v_bfe_u32 v22, v35, 16, 1
	v_lshrrev_b32_e32 v19, 16, v19
	v_add3_u32 v22, v35, v22, s87
	v_and_or_b32 v22, v22, s90, v19
	v_bfe_u32 v19, v37, 16, 1
	v_add3_u32 v19, v37, v19, s87
	v_bfe_u32 v23, v39, 16, 1
	v_lshrrev_b32_e32 v19, 16, v19
	v_add3_u32 v23, v39, v23, s87
	v_and_or_b32 v23, v23, s90, v19
	v_or_b32_e32 v19, s4, v15
	v_lshlrev_b32_e32 v24, 7, v19
	v_mov_b32_e32 v25, v2
	ds_read2_b32 v[26:27], v10 offset0:48 offset1:56
	v_lshl_add_u64 v[24:25], v[8:9], 0, v[24:25]
	global_store_dwordx4 v[24:25], v[20:23], off
	ds_read2_b32 v[24:25], v10 offset0:113 offset1:121
	ds_read2_b32 v[28:29], v10 offset0:178 offset1:186
	ds_read2_b32 v[30:31], v10 offset0:243 offset1:251
	s_waitcnt lgkmcnt(3)
	v_bfe_u32 v19, v26, 16, 1
	v_add3_u32 v19, v26, v19, s87
	s_waitcnt lgkmcnt(2)
	v_bfe_u32 v20, v24, 16, 1
	ds_read2_b32 v[32:33], v42 offset0:52 offset1:60
	v_lshrrev_b32_e32 v19, 16, v19
	v_add3_u32 v20, v24, v20, s87
	ds_read2_b32 v[34:35], v42 offset0:117 offset1:125
	v_and_or_b32 v20, v20, s90, v19
	s_waitcnt lgkmcnt(3)
	v_bfe_u32 v19, v28, 16, 1
	v_add3_u32 v19, v28, v19, s87
	s_waitcnt lgkmcnt(2)
	v_bfe_u32 v21, v30, 16, 1
	ds_read2_b32 v[36:37], v42 offset0:182 offset1:190
	v_lshrrev_b32_e32 v19, 16, v19
	v_add3_u32 v21, v30, v21, s87
	ds_read2_b32 v[38:39], v42 offset0:247 offset1:255
	v_and_or_b32 v21, v21, s90, v19
	s_waitcnt lgkmcnt(3)
	v_bfe_u32 v19, v32, 16, 1
	v_add3_u32 v19, v32, v19, s87
	s_waitcnt lgkmcnt(2)
	v_bfe_u32 v22, v34, 16, 1
	v_lshrrev_b32_e32 v19, 16, v19
	v_add3_u32 v22, v34, v22, s87
	v_and_or_b32 v22, v22, s90, v19
	s_waitcnt lgkmcnt(1)
	v_bfe_u32 v19, v36, 16, 1
	v_add3_u32 v19, v36, v19, s87
	s_waitcnt lgkmcnt(0)
	v_bfe_u32 v23, v38, 16, 1
	v_lshrrev_b32_e32 v19, 16, v19
	v_add3_u32 v23, v38, v23, s87
	v_and_or_b32 v23, v23, s90, v19
	v_or_b32_e32 v19, s4, v16
	v_lshlrev_b32_e32 v40, 7, v19
	v_mov_b32_e32 v41, v2
	v_lshl_add_u64 v[40:41], v[8:9], 0, v[40:41]
	v_bfe_u32 v19, v27, 16, 1
	global_store_dwordx4 v[40:41], v[20:23], off
	v_add3_u32 v19, v27, v19, s87
	v_lshrrev_b32_e32 v19, 16, v19
	v_bfe_u32 v20, v25, 16, 1
	v_add3_u32 v20, v25, v20, s87
	v_and_or_b32 v20, v20, s90, v19
	v_bfe_u32 v19, v29, 16, 1
	v_add3_u32 v19, v29, v19, s87
	v_bfe_u32 v21, v31, 16, 1
	v_lshrrev_b32_e32 v19, 16, v19
	v_add3_u32 v21, v31, v21, s87
	v_and_or_b32 v21, v21, s90, v19
	v_bfe_u32 v19, v33, 16, 1
	v_add3_u32 v19, v33, v19, s87
	v_bfe_u32 v22, v35, 16, 1
	v_lshrrev_b32_e32 v19, 16, v19
	v_add3_u32 v22, v35, v22, s87
	v_and_or_b32 v22, v22, s90, v19
	v_bfe_u32 v19, v37, 16, 1
	v_add3_u32 v19, v37, v19, s87
	v_bfe_u32 v23, v39, 16, 1
	v_lshrrev_b32_e32 v19, 16, v19
	v_add3_u32 v23, v39, v23, s87
	v_and_or_b32 v23, v23, s90, v19
	v_or_b32_e32 v19, s4, v17
	v_lshlrev_b32_e32 v24, 7, v19
	v_mov_b32_e32 v25, v2
	v_lshl_add_u64 v[8:9], v[8:9], 0, v[24:25]
	global_store_dwordx4 v[8:9], v[20:23], off
	s_waitcnt lgkmcnt(0)
	s_branch .LBB0_359
